# NA-in GEMM: units ordered in groups of four column tiles so an XCD keeps 2 MiB of weights in L2 instead of streaming all 8 MiB every round
# speedup vs baseline: 1.0112x; 1.0112x over previous
;     __device__ __forceinline__ bool next(int i, Unit& u) const {
;         const int L = i * G + (((i + 1) * G <= n) ? c : cp); if (L >= n) return false;
;         if (mode == 0) { u.pm = L / nN; u.pn = L - u.pm * nN; }
;     ...
;         } else if (mode == 4) { const int nn = L / 272, rem = L - nn * 272; u.pm = rem >> 2; u.pn = nn * 4 + (rem & 3); }
.LBB0_917:
	s_cmp_lt_i32 s34, 10
	s_cselect_b64 s[6:7], -1, 0
	s_cmp_gt_i32 s35, 9
	s_cselect_b64 s[8:9], -1, 0
	s_and_b64 s[6:7], s[6:7], s[8:9]
	s_andn2_b64 vcc, exec, s[6:7]
	s_cbranch_vccnz .LBB0_1000
	s_lshl_b32 s3, s2, 5
	s_and_b32 s3, s3, 0xe0
	s_ashr_i32 s6, s2, 3
	s_add_i32 s3, s3, s6
	s_cmpk_eq_i32 s30, 0x100
	s_cselect_b32 s3, s3, s2
	s_cmpk_gt_i32 s30, 0x440
	s_cselect_b32 s7, s2, s3
	s_cmpk_gt_i32 s7, 0x43f
	s_cbranch_scc1 .Lnord_a
	s_cmpk_gt_u32 s7, 0x10f
	s_cselect_b32 s94, 1, 0
	s_cmpk_gt_u32 s7, 0x21f
	s_cselect_b32 s95, 1, 0
	s_add_i32 s94, s94, s95
	s_cmpk_gt_u32 s7, 0x32f
	s_cselect_b32 s95, 1, 0
	s_add_i32 s94, s94, s95
	s_mul_i32 s95, s94, 0x110
	s_sub_i32 s95, s7, s95
	s_lshl_b32 s94, s94, 2
	s_lshr_b32 s7, s95, 2
	s_lshl_b32 s7, s7, 4
	s_and_b32 s95, s95, 3
	s_add_i32 s94, s94, s95
	s_add_i32 s7, s7, s94
.Lnord_a:
	s_cmpk_lt_i32 s7, 0x440
	s_cselect_b64 s[8:9], -1, 0
	s_cmpk_gt_i32 s7, 0x43f
	v_readfirstlane_b32 s14, v128
	s_cbranch_scc1 .LBB0_920
	s_ashr_i32 s6, s7, 31
	s_lshr_b32 s6, s6, 28
	s_add_i32 s10, s7, s6
	s_ashr_i32 s6, s10, 4
	s_and_b32 s10, s10, -16
	s_sub_i32 s42, s7, s10

;     __device__ __forceinline__ bool next(int i, Unit& u) const {
;         const int L = i * G + (((i + 1) * G <= n) ? c : cp); if (L >= n) return false;
;         if (mode == 0) { u.pm = L / nN; u.pn = L - u.pm * nN; }
;     ...
;         } else if (mode == 4) { const int nn = L / 272, rem = L - nn * 272; u.pm = rem >> 2; u.pn = nn * 4 + (rem & 3); }
.LBB0_926:
	s_add_i32 s60, s60, 1
	s_mul_i32 s7, s60, s30
	s_add_i32 s17, s7, s30
	s_cmpk_gt_i32 s17, 0x440
	s_cselect_b32 s17, s2, s3
	s_add_i32 s7, s17, s7
	s_cmpk_gt_i32 s7, 0x43f
	s_cbranch_scc1 .Lnord_b
	s_cmpk_gt_u32 s7, 0x10f
	s_cselect_b32 s94, 1, 0
	s_cmpk_gt_u32 s7, 0x21f
	s_cselect_b32 s95, 1, 0
	s_add_i32 s94, s94, s95
	s_cmpk_gt_u32 s7, 0x32f
	s_cselect_b32 s95, 1, 0
	s_add_i32 s94, s94, s95
	s_mul_i32 s95, s94, 0x110
	s_sub_i32 s95, s7, s95
	s_lshl_b32 s94, s94, 2
	s_lshr_b32 s7, s95, 2
	s_lshl_b32 s7, s7, 4
	s_and_b32 s95, s95, 3
	s_add_i32 s94, s94, s95
	s_add_i32 s7, s7, s94
